# attention tile loops rotated: ring rotation, counter and loop test moved ahead of the closing wait and barrier (byte phase kept)
# speedup vs baseline: 1.0080x; 1.0080x over previous
.Lat2_unit_1:
	s_and_b32 s4, s38, 3
	s_lshl_b32 s4, s4, 1
	s_lshr_b32 s5, s26, 1
	s_add_i32 s4, s4, s5
	s_sub_i32 s5, 15, s4
	s_bitcmp1_b32 s26, 0
	s_cselect_b32 s4, s4, s5
	s_lshl_b32 s39, s4, 2
	s_add_i32 s39, s39, 4
	s_sub_i32 s18, s39, 4
	s_lshr_b32 s5, s38, 5
	s_lshl_b32 s5, s5, 12
	s_lshl_b32 s6, s4, 8
	s_add_i32 s6, s6, s5
	s_bfe_u32 s7, s38, 0x30002
	s_lshl_b32 s14, s6, 10
	s_lshl_b32 s15, s7, 7
	s_add_i32 s14, s14, s15
	s_add_u32 s72, s54, s14
	s_addc_u32 s73, s55, 0
	s_lshl_b32 s14, s5, 10
	s_add_i32 s15, s14, s15
	s_add_i32 s15, s15, 0x2000000
	s_add_u32 s74, s54, s15
	s_addc_u32 s75, s55, 0
	s_lshr_b32 s15, s7, 1
	s_lshl_b32 s15, s15, 8
	s_add_i32 s14, s14, s15
	s_add_u32 s76, s64, s14
	s_addc_u32 s77, s65, 0
	s_lshl_b32 s14, s6, 11
	s_lshl_b32 s15, s7, 8
	s_add_i32 s14, s14, s15
	s_add_u32 s78, s50, s14
	s_addc_u32 s79, s51, 0
	global_load_dwordx4 v[148:151], v225, s[72:73] offset:0
	global_load_dwordx4 v[152:155], v225, s[72:73] offset:32
	global_load_dwordx4 v[156:159], v225, s[72:73] offset:64
	global_load_dwordx4 v[160:163], v225, s[72:73] offset:96
	s_mov_b64 s[80:81], s[74:75]
	s_mov_b64 s[82:83], s[76:77]
	s_mov_b32 s59, 0
	s_mov_b32 s60, 0x2000
	s_mov_b32 s61, 0x4000
	s_mov_b32 s25, 0x6000
	s_add_i32 s4, s59, s16
	s_mov_b32 m0, s4
	s_lshl_b32 s5, s59, 1
	global_load_lds_dwordx4 v200, s[80:81]
	s_add_i32 s5, s5, s16
	s_add_i32 s5, s5, 0x8000
	s_mov_b32 m0, s5
	s_add_i32 s5, s5, 0x2000
	global_load_lds_dwordx4 v201, s[82:83]
	s_mov_b32 m0, s5
	s_nop 0
	global_load_lds_dwordx4 v202, s[82:83]
	s_add_u32 s80, s80, 0x10000
	s_addc_u32 s81, s81, 0
	s_add_u32 s82, s82, 0x10000
	s_addc_u32 s83, s83, 0
	s_add_i32 s4, s60, s16
	s_mov_b32 m0, s4
	s_lshl_b32 s5, s60, 1
	global_load_lds_dwordx4 v200, s[80:81]
	s_add_i32 s5, s5, s16
	s_add_i32 s5, s5, 0x8000
	s_mov_b32 m0, s5
	s_add_i32 s5, s5, 0x2000
	global_load_lds_dwordx4 v201, s[82:83]
	s_mov_b32 m0, s5
	s_nop 0
	global_load_lds_dwordx4 v202, s[82:83]
	s_add_u32 s80, s80, 0x10000
	s_addc_u32 s81, s81, 0
	s_add_u32 s82, s82, 0x10000
	s_addc_u32 s83, s83, 0
	s_add_i32 s4, s61, s16
	s_mov_b32 m0, s4
	s_lshl_b32 s5, s61, 1
	global_load_lds_dwordx4 v200, s[80:81]
	s_add_i32 s5, s5, s16
	s_add_i32 s5, s5, 0x8000
	s_mov_b32 m0, s5
	s_add_i32 s5, s5, 0x2000
	global_load_lds_dwordx4 v201, s[82:83]
	s_mov_b32 m0, s5
	s_nop 0
	global_load_lds_dwordx4 v202, s[82:83]
	s_add_u32 s80, s80, 0x10000
	s_addc_u32 s81, s81, 0
	s_add_u32 s82, s82, 0x10000
	s_addc_u32 s83, s83, 0
	v_mov_b32_e32 v0, 0
	v_mov_b32_e32 v1, 0
	v_mov_b32_e32 v2, 0
	v_mov_b32_e32 v3, 0
	v_mov_b32_e32 v4, 0
	v_mov_b32_e32 v5, 0
	v_mov_b32_e32 v6, 0
	v_mov_b32_e32 v7, 0
	v_mov_b32_e32 v8, 0
	v_mov_b32_e32 v9, 0
	v_mov_b32_e32 v10, 0
	v_mov_b32_e32 v11, 0
	v_mov_b32_e32 v12, 0
	v_mov_b32_e32 v13, 0
	v_mov_b32_e32 v14, 0
	v_mov_b32_e32 v15, 0
	v_mov_b32_e32 v16, 0
	v_mov_b32_e32 v17, 0
	v_mov_b32_e32 v18, 0
	v_mov_b32_e32 v19, 0
	v_mov_b32_e32 v20, 0
	v_mov_b32_e32 v21, 0
	v_mov_b32_e32 v22, 0
	v_mov_b32_e32 v23, 0
	v_mov_b32_e32 v24, 0
	v_mov_b32_e32 v25, 0
	v_mov_b32_e32 v26, 0
	v_mov_b32_e32 v27, 0
	v_mov_b32_e32 v28, 0
	v_mov_b32_e32 v29, 0
	v_mov_b32_e32 v30, 0
	v_mov_b32_e32 v31, 0
	v_mov_b32_e32 v32, 0
	v_mov_b32_e32 v33, 0
	v_mov_b32_e32 v34, 0
	v_mov_b32_e32 v35, 0
	v_mov_b32_e32 v36, 0
	v_mov_b32_e32 v37, 0
	v_mov_b32_e32 v38, 0
	v_mov_b32_e32 v39, 0
	v_mov_b32_e32 v40, 0
	v_mov_b32_e32 v41, 0
	v_mov_b32_e32 v42, 0
	v_mov_b32_e32 v43, 0
	v_mov_b32_e32 v44, 0
	v_mov_b32_e32 v45, 0
	v_mov_b32_e32 v46, 0
	v_mov_b32_e32 v47, 0
	v_mov_b32_e32 v48, 0
	v_mov_b32_e32 v49, 0
	v_mov_b32_e32 v50, 0
	v_mov_b32_e32 v51, 0
	v_mov_b32_e32 v52, 0
	v_mov_b32_e32 v53, 0
	v_mov_b32_e32 v54, 0
	v_mov_b32_e32 v55, 0
	v_mov_b32_e32 v56, 0
	v_mov_b32_e32 v57, 0
	v_mov_b32_e32 v58, 0
	v_mov_b32_e32 v59, 0
	v_mov_b32_e32 v60, 0
	v_mov_b32_e32 v61, 0
	v_mov_b32_e32 v62, 0
	v_mov_b32_e32 v63, 0
	v_mov_b32_e32 v100, 0
	v_mov_b32_e32 v101, 0
	v_mov_b32_e32 v102, 0
	v_mov_b32_e32 v103, 0
	v_mov_b32_e32 v104, 0
	v_mov_b32_e32 v105, 0
	v_mov_b32_e32 v106, 0
	v_mov_b32_e32 v107, 0
	v_mov_b32_e32 v108, 0
	v_mov_b32_e32 v109, 0
	v_mov_b32_e32 v110, 0
	v_mov_b32_e32 v111, 0
	v_mov_b32_e32 v112, 0
	v_mov_b32_e32 v113, 0
	v_mov_b32_e32 v114, 0
	v_mov_b32_e32 v115, 0
	v_mov_b32_e32 v210, 0
	v_mov_b32_e32 v232, 0
	v_mov_b32_e32 v233, 0
	v_mov_b32_e32 v234, 0
	v_mov_b32_e32 v235, 0
	s_mov_b32 s62, 0xf149f2ca
	s_mov_b32 s47, 0xf149f2ca
	s_mov_b32 s45, 0
	s_waitcnt vmcnt(6)
	s_barrier
	s_cmp_lt_u32 s45, s18
	s_cbranch_scc0 .Lat2_band_3
.Lat2_main_2:
	v_add_u32_e32 v205, s59, v203
	ds_read_b128 v[116:119], v205 offset:0
	ds_read_b128 v[120:123], v205 offset:512
	ds_read_b128 v[124:127], v205 offset:2048
	ds_read_b128 v[128:131], v205 offset:2560
	ds_read_b128 v[132:135], v205 offset:4096
	ds_read_b128 v[136:139], v205 offset:4608
	ds_read_b128 v[140:143], v205 offset:6144
	ds_read_b128 v[144:147], v205 offset:6656
	s_add_i32 s6, s45, 3
	s_cmp_lt_u32 s6, s39
	s_cbranch_scc0 .Lat2_nodma_6
	s_add_i32 s4, s25, s16
	s_mov_b32 m0, s4
	s_lshl_b32 s5, s25, 1
	global_load_lds_dwordx4 v200, s[80:81]
	s_add_i32 s5, s5, s16
	s_add_i32 s5, s5, 0x8000
	s_mov_b32 m0, s5
	s_add_i32 s5, s5, 0x2000
	global_load_lds_dwordx4 v201, s[82:83]
	s_mov_b32 m0, s5
	s_nop 0
	global_load_lds_dwordx4 v202, s[82:83]
	s_add_u32 s80, s80, 0x10000
	s_addc_u32 s81, s81, 0
	s_add_u32 s82, s82, 0x10000
	s_addc_u32 s83, s83, 0

.Lat2_back_8:
	v_exp_f32_e32 v64, v64
	v_exp_f32_e32 v65, v65
	v_exp_f32_e32 v66, v66
	v_exp_f32_e32 v67, v67
	v_exp_f32_e32 v68, v68
	v_exp_f32_e32 v69, v69
	v_exp_f32_e32 v70, v70
	v_exp_f32_e32 v71, v71
	s_nop 0
	v_pk_add_f32 v[232:233], v[232:233], v[64:65]
	v_pk_add_f32 v[234:235], v[234:235], v[66:67]
	v_pk_add_f32 v[232:233], v[232:233], v[68:69]
	v_pk_add_f32 v[234:235], v[234:235], v[70:71]
	v_cvt_pk_bf16_f32 v64, v64, v65
	v_cvt_pk_bf16_f32 v65, v66, v67
	v_cvt_pk_bf16_f32 v66, v68, v69
	v_cvt_pk_bf16_f32 v67, v70, v71
	s_waitcnt lgkmcnt(0)
	s_nop 0
	v_mfma_f32_32x32x16_bf16 v[0:15], v[64:67], v[164:167], v[0:15]
	v_exp_f32_e32 v72, v72
	v_exp_f32_e32 v73, v73
	v_mfma_f32_32x32x16_bf16 v[16:31], v[64:67], v[168:171], v[16:31]
	ds_read_b64_tr_b16 v[164:165], v206 offset:2048
	ds_read_b64_tr_b16 v[166:167], v206 offset:2560
	v_exp_f32_e32 v74, v74
	v_exp_f32_e32 v75, v75
	v_pk_add_f32 v[232:233], v[232:233], v[72:73]
	v_mfma_f32_32x32x16_bf16 v[32:47], v[64:67], v[172:175], v[32:47]
	ds_read_b64_tr_b16 v[168:169], v206 offset:6144
	ds_read_b64_tr_b16 v[170:171], v206 offset:6656
	v_exp_f32_e32 v76, v76
	v_exp_f32_e32 v77, v77
	v_pk_add_f32 v[234:235], v[234:235], v[74:75]
	v_mfma_f32_32x32x16_bf16 v[48:63], v[64:67], v[176:179], v[48:63]
	ds_read_b64_tr_b16 v[172:173], v206 offset:10240
	ds_read_b64_tr_b16 v[174:175], v206 offset:10752
	v_exp_f32_e32 v78, v78
	v_exp_f32_e32 v79, v79
	v_pk_add_f32 v[232:233], v[232:233], v[76:77]
	s_nop 0
	v_pk_add_f32 v[234:235], v[234:235], v[78:79]
	v_cvt_pk_bf16_f32 v72, v72, v73
	v_cvt_pk_bf16_f32 v73, v74, v75
	v_cvt_pk_bf16_f32 v74, v76, v77
	v_cvt_pk_bf16_f32 v75, v78, v79
	s_nop 1
	v_mfma_f32_32x32x16_bf16 v[0:15], v[72:75], v[180:183], v[0:15]
	ds_read_b64_tr_b16 v[176:177], v206 offset:14336
	ds_read_b64_tr_b16 v[178:179], v206 offset:14848
	v_exp_f32_e32 v80, v80
	v_exp_f32_e32 v81, v81
	v_mfma_f32_32x32x16_bf16 v[16:31], v[72:75], v[184:187], v[16:31]
	ds_read_b64_tr_b16 v[180:181], v206 offset:3072
	ds_read_b64_tr_b16 v[182:183], v206 offset:3584
	v_exp_f32_e32 v82, v82
	v_exp_f32_e32 v83, v83
	v_pk_add_f32 v[232:233], v[232:233], v[80:81]
	v_mfma_f32_32x32x16_bf16 v[32:47], v[72:75], v[188:191], v[32:47]
	ds_read_b64_tr_b16 v[184:185], v206 offset:7168
	ds_read_b64_tr_b16 v[186:187], v206 offset:7680
	v_exp_f32_e32 v84, v84
	v_exp_f32_e32 v85, v85
	v_pk_add_f32 v[234:235], v[234:235], v[82:83]
	v_mfma_f32_32x32x16_bf16 v[48:63], v[72:75], v[192:195], v[48:63]
	ds_read_b64_tr_b16 v[188:189], v206 offset:11264
	ds_read_b64_tr_b16 v[190:191], v206 offset:11776
	v_exp_f32_e32 v86, v86
	v_exp_f32_e32 v87, v87
	v_pk_add_f32 v[232:233], v[232:233], v[84:85]
	s_nop 0
	v_pk_add_f32 v[234:235], v[234:235], v[86:87]
	v_cvt_pk_bf16_f32 v80, v80, v81
	v_cvt_pk_bf16_f32 v81, v82, v83
	v_cvt_pk_bf16_f32 v82, v84, v85
	v_cvt_pk_bf16_f32 v83, v86, v87
	s_nop 1
	s_waitcnt lgkmcnt(12)
	v_mfma_f32_32x32x16_bf16 v[0:15], v[80:83], v[164:167], v[0:15]
	ds_read_b64_tr_b16 v[192:193], v206 offset:15360
	ds_read_b64_tr_b16 v[194:195], v206 offset:15872
	v_exp_f32_e32 v88, v88
	v_exp_f32_e32 v89, v89
	s_waitcnt lgkmcnt(12)
	v_mfma_f32_32x32x16_bf16 v[16:31], v[80:83], v[168:171], v[16:31]
	v_exp_f32_e32 v90, v90
	v_exp_f32_e32 v91, v91
	v_pk_add_f32 v[232:233], v[232:233], v[88:89]
	s_waitcnt lgkmcnt(10)
	v_mfma_f32_32x32x16_bf16 v[32:47], v[80:83], v[172:175], v[32:47]
	v_exp_f32_e32 v92, v92
	v_exp_f32_e32 v93, v93
	v_pk_add_f32 v[234:235], v[234:235], v[90:91]
	s_waitcnt lgkmcnt(8)
	v_mfma_f32_32x32x16_bf16 v[48:63], v[80:83], v[176:179], v[48:63]
	v_exp_f32_e32 v94, v94
	v_exp_f32_e32 v95, v95
	v_pk_add_f32 v[232:233], v[232:233], v[92:93]
	s_nop 0
	v_pk_add_f32 v[234:235], v[234:235], v[94:95]
	v_cvt_pk_bf16_f32 v88, v88, v89
	v_cvt_pk_bf16_f32 v89, v90, v91
	v_cvt_pk_bf16_f32 v90, v92, v93
	v_cvt_pk_bf16_f32 v91, v94, v95
	s_nop 1
	s_waitcnt lgkmcnt(6)
	v_mfma_f32_32x32x16_bf16 v[0:15], v[88:91], v[180:183], v[0:15]
	s_waitcnt lgkmcnt(4)
	v_mfma_f32_32x32x16_bf16 v[16:31], v[88:91], v[184:187], v[16:31]
	s_waitcnt lgkmcnt(2)
	v_mfma_f32_32x32x16_bf16 v[32:47], v[88:91], v[188:191], v[32:47]
	s_waitcnt lgkmcnt(0)
	v_mfma_f32_32x32x16_bf16 v[48:63], v[88:91], v[192:195], v[48:63]
	s_mov_b32 s4, s59
	s_mov_b32 s59, s60
	s_mov_b32 s60, s61
	s_mov_b32 s61, s25
	s_mov_b32 s25, s4
	s_add_i32 s45, s45, 1
	s_mov_b32 s62, 0x41000000
	s_mov_b32 s47, 0
	s_add_i32 s6, s45, 2
	s_cmp_lt_u32 s6, s39
	s_cbranch_scc1 .Lat2_w6_16
	s_cmp_eq_u32 s6, s39
	s_cbranch_scc1 .Lat2_w3_14
	s_waitcnt vmcnt(0)
	s_branch .Lat2_wd_15

.Lat2_wd_15:
	s_cmp_lt_u32 s45, s18
	s_waitcnt lgkmcnt(0)
	s_barrier
	s_cbranch_scc1 .Lat2_main_2
.Lat2_skip_13:
	s_nop 0
.Lat2_band_3:
.Lat2_bandloop_4:
	s_sub_i32 s19, s45, s18
	s_add_i32 s6, s45, 3
	s_cmp_lt_u32 s6, s39
	s_cbranch_scc0 .Lat2_nodma_17
	s_add_i32 s4, s25, s16
	s_mov_b32 m0, s4
	s_lshl_b32 s5, s25, 1
	global_load_lds_dwordx4 v200, s[80:81]
	s_add_i32 s5, s5, s16
	s_add_i32 s5, s5, 0x8000
	s_mov_b32 m0, s5
	s_add_i32 s5, s5, 0x2000
	global_load_lds_dwordx4 v201, s[82:83]
	s_mov_b32 m0, s5
	s_nop 0
	global_load_lds_dwordx4 v202, s[82:83]
	s_add_u32 s80, s80, 0x10000
	s_addc_u32 s81, s81, 0
	s_add_u32 s82, s82, 0x10000
	s_addc_u32 s83, s83, 0

.Lat2_allmasked_20:
	s_mov_b32 s4, s59
	s_mov_b32 s59, s60
	s_mov_b32 s60, s61
	s_mov_b32 s61, s25
	s_mov_b32 s25, s4
	s_add_i32 s45, s45, 1
	s_mov_b32 s62, 0x41000000
	s_mov_b32 s47, 0
	s_add_i32 s6, s45, 2
	s_cmp_lt_u32 s6, s39
	s_cbranch_scc1 .Lat2_w6_27
	s_cmp_eq_u32 s6, s39
	s_cbranch_scc1 .Lat2_w3_25
	s_waitcnt vmcnt(0)
	s_branch .Lat2_wd_26

.Lat2_wd_26:
	s_cmp_lt_u32 s45, s39
	s_waitcnt lgkmcnt(0)
	s_barrier
	s_cbranch_scc1 .Lat2_bandloop_4
.Lat2_skip_24:
	v_add_f32_e32 v232, v232, v233
	v_add_f32_e32 v234, v234, v235
	v_add_f32_e32 v216, v232, v234
	v_mov_b32_e32 v215, v216
	s_nop 1
	v_permlane32_swap_b32_e32 v216, v215
	s_nop 0
	v_add_f32_e32 v216, v216, v215
	v_rcp_f32_e32 v217, v216
	s_nop 0
	ds_write_b32 v220, v217
	s_waitcnt lgkmcnt(0)
	ds_read_b128 v[116:119], v221 offset:0
	ds_read_b128 v[120:123], v221 offset:32
	ds_read_b128 v[124:127], v221 offset:64
	ds_read_b128 v[128:131], v221 offset:96
	v_add_u32_e32 v229, 0x8000, v224
	s_waitcnt lgkmcnt(0)
	v_mul_f32_e32 v0, v0, v116
	v_mul_f32_e32 v1, v1, v117
	v_cvt_pk_bf16_f32 v0, v0, v1
	ds_write_b16 v222, v0 offset:0
	ds_write_b16_d16_hi v222, v0 offset:64
	v_mul_f32_e32 v2, v2, v118
	v_mul_f32_e32 v3, v3, v119
	v_cvt_pk_bf16_f32 v2, v2, v3
	ds_write_b16 v222, v2 offset:128
	ds_write_b16_d16_hi v222, v2 offset:192
	v_mul_f32_e32 v4, v4, v120
	v_mul_f32_e32 v5, v5, v121
	v_cvt_pk_bf16_f32 v4, v4, v5
	ds_write_b16 v222, v4 offset:512
	ds_write_b16_d16_hi v222, v4 offset:576
	v_mul_f32_e32 v6, v6, v122
	v_mul_f32_e32 v7, v7, v123
	v_cvt_pk_bf16_f32 v6, v6, v7
	ds_write_b16 v222, v6 offset:640
	ds_write_b16_d16_hi v222, v6 offset:704
	v_mul_f32_e32 v8, v8, v124
	v_mul_f32_e32 v9, v9, v125
	v_cvt_pk_bf16_f32 v8, v8, v9
	ds_write_b16 v222, v8 offset:1024
	ds_write_b16_d16_hi v222, v8 offset:1088
	v_mul_f32_e32 v10, v10, v126
	v_mul_f32_e32 v11, v11, v127
	v_cvt_pk_bf16_f32 v10, v10, v11
	ds_write_b16 v222, v10 offset:1152
	ds_write_b16_d16_hi v222, v10 offset:1216
	v_mul_f32_e32 v12, v12, v128
	v_mul_f32_e32 v13, v13, v129
	v_cvt_pk_bf16_f32 v12, v12, v13
	ds_write_b16 v222, v12 offset:1536
	ds_write_b16_d16_hi v222, v12 offset:1600
	v_mul_f32_e32 v14, v14, v130
	v_mul_f32_e32 v15, v15, v131
	v_cvt_pk_bf16_f32 v14, v14, v15
	ds_write_b16 v222, v14 offset:1664
	ds_write_b16_d16_hi v222, v14 offset:1728
	s_waitcnt lgkmcnt(0)
	ds_read_b128 v[132:135], v223
	ds_read_b128 v[136:139], v223 offset:1024
	s_waitcnt lgkmcnt(1)
	global_store_dwordx4 v224, v[132:135], s[78:79] offset:0
	s_waitcnt lgkmcnt(0)
	global_store_dwordx4 v229, v[136:139], s[78:79] offset:0
	v_mul_f32_e32 v16, v16, v116
	v_mul_f32_e32 v17, v17, v117
	v_cvt_pk_bf16_f32 v16, v16, v17
	ds_write_b16 v222, v16 offset:0
	ds_write_b16_d16_hi v222, v16 offset:64
	v_mul_f32_e32 v18, v18, v118
	v_mul_f32_e32 v19, v19, v119
	v_cvt_pk_bf16_f32 v18, v18, v19
	ds_write_b16 v222, v18 offset:128
	ds_write_b16_d16_hi v222, v18 offset:192
	v_mul_f32_e32 v20, v20, v120
	v_mul_f32_e32 v21, v21, v121
	v_cvt_pk_bf16_f32 v20, v20, v21
	ds_write_b16 v222, v20 offset:512
	ds_write_b16_d16_hi v222, v20 offset:576
	v_mul_f32_e32 v22, v22, v122
	v_mul_f32_e32 v23, v23, v123
	v_cvt_pk_bf16_f32 v22, v22, v23
	ds_write_b16 v222, v22 offset:640
	ds_write_b16_d16_hi v222, v22 offset:704
	v_mul_f32_e32 v24, v24, v124
	v_mul_f32_e32 v25, v25, v125
	v_cvt_pk_bf16_f32 v24, v24, v25
	ds_write_b16 v222, v24 offset:1024
	ds_write_b16_d16_hi v222, v24 offset:1088
	v_mul_f32_e32 v26, v26, v126
	v_mul_f32_e32 v27, v27, v127
	v_cvt_pk_bf16_f32 v26, v26, v27
	ds_write_b16 v222, v26 offset:1152
	ds_write_b16_d16_hi v222, v26 offset:1216
	v_mul_f32_e32 v28, v28, v128
	v_mul_f32_e32 v29, v29, v129
	v_cvt_pk_bf16_f32 v28, v28, v29
	ds_write_b16 v222, v28 offset:1536
	ds_write_b16_d16_hi v222, v28 offset:1600
	v_mul_f32_e32 v30, v30, v130
	v_mul_f32_e32 v31, v31, v131
	v_cvt_pk_bf16_f32 v30, v30, v31
	ds_write_b16 v222, v30 offset:1664
	ds_write_b16_d16_hi v222, v30 offset:1728
	s_waitcnt lgkmcnt(0)
	ds_read_b128 v[132:135], v223
	ds_read_b128 v[136:139], v223 offset:1024
	s_waitcnt lgkmcnt(1)
	global_store_dwordx4 v224, v[132:135], s[78:79] offset:64
	s_waitcnt lgkmcnt(0)
	global_store_dwordx4 v229, v[136:139], s[78:79] offset:64
	v_mul_f32_e32 v32, v32, v116
	v_mul_f32_e32 v33, v33, v117
	v_cvt_pk_bf16_f32 v32, v32, v33
	ds_write_b16 v222, v32 offset:0
	ds_write_b16_d16_hi v222, v32 offset:64
	v_mul_f32_e32 v34, v34, v118
	v_mul_f32_e32 v35, v35, v119
	v_cvt_pk_bf16_f32 v34, v34, v35
	ds_write_b16 v222, v34 offset:128
	ds_write_b16_d16_hi v222, v34 offset:192
	v_mul_f32_e32 v36, v36, v120
	v_mul_f32_e32 v37, v37, v121
	v_cvt_pk_bf16_f32 v36, v36, v37
	ds_write_b16 v222, v36 offset:512
	ds_write_b16_d16_hi v222, v36 offset:576
	v_mul_f32_e32 v38, v38, v122
	v_mul_f32_e32 v39, v39, v123
	v_cvt_pk_bf16_f32 v38, v38, v39
	ds_write_b16 v222, v38 offset:640
	ds_write_b16_d16_hi v222, v38 offset:704
	v_mul_f32_e32 v40, v40, v124
	v_mul_f32_e32 v41, v41, v125
	v_cvt_pk_bf16_f32 v40, v40, v41
	ds_write_b16 v222, v40 offset:1024
	ds_write_b16_d16_hi v222, v40 offset:1088
	v_mul_f32_e32 v42, v42, v126
	v_mul_f32_e32 v43, v43, v127
	v_cvt_pk_bf16_f32 v42, v42, v43
	ds_write_b16 v222, v42 offset:1152
	ds_write_b16_d16_hi v222, v42 offset:1216
	v_mul_f32_e32 v44, v44, v128
	v_mul_f32_e32 v45, v45, v129
	v_cvt_pk_bf16_f32 v44, v44, v45
	ds_write_b16 v222, v44 offset:1536
	ds_write_b16_d16_hi v222, v44 offset:1600
	v_mul_f32_e32 v46, v46, v130
	v_mul_f32_e32 v47, v47, v131
	v_cvt_pk_bf16_f32 v46, v46, v47
	ds_write_b16 v222, v46 offset:1664
	ds_write_b16_d16_hi v222, v46 offset:1728
	s_waitcnt lgkmcnt(0)
	ds_read_b128 v[132:135], v223
	ds_read_b128 v[136:139], v223 offset:1024
	s_waitcnt lgkmcnt(1)
	global_store_dwordx4 v224, v[132:135], s[78:79] offset:128
	s_waitcnt lgkmcnt(0)
	global_store_dwordx4 v229, v[136:139], s[78:79] offset:128
	v_mul_f32_e32 v48, v48, v116
	v_mul_f32_e32 v49, v49, v117
	v_cvt_pk_bf16_f32 v48, v48, v49
	ds_write_b16 v222, v48 offset:0
	ds_write_b16_d16_hi v222, v48 offset:64
	v_mul_f32_e32 v50, v50, v118
	v_mul_f32_e32 v51, v51, v119
	v_cvt_pk_bf16_f32 v50, v50, v51
	ds_write_b16 v222, v50 offset:128
	ds_write_b16_d16_hi v222, v50 offset:192
	v_mul_f32_e32 v52, v52, v120
	v_mul_f32_e32 v53, v53, v121
	v_cvt_pk_bf16_f32 v52, v52, v53
	ds_write_b16 v222, v52 offset:512
	ds_write_b16_d16_hi v222, v52 offset:576
	v_mul_f32_e32 v54, v54, v122
	v_mul_f32_e32 v55, v55, v123
	v_cvt_pk_bf16_f32 v54, v54, v55
	ds_write_b16 v222, v54 offset:640
	ds_write_b16_d16_hi v222, v54 offset:704
	v_mul_f32_e32 v56, v56, v124
	v_mul_f32_e32 v57, v57, v125
	v_cvt_pk_bf16_f32 v56, v56, v57
	ds_write_b16 v222, v56 offset:1024
	ds_write_b16_d16_hi v222, v56 offset:1088
	v_mul_f32_e32 v58, v58, v126
	v_mul_f32_e32 v59, v59, v127
	v_cvt_pk_bf16_f32 v58, v58, v59
	ds_write_b16 v222, v58 offset:1152
	ds_write_b16_d16_hi v222, v58 offset:1216
	v_mul_f32_e32 v60, v60, v128
	v_mul_f32_e32 v61, v61, v129
	v_cvt_pk_bf16_f32 v60, v60, v61
	ds_write_b16 v222, v60 offset:1536
	ds_write_b16_d16_hi v222, v60 offset:1600
	v_mul_f32_e32 v62, v62, v130
	v_mul_f32_e32 v63, v63, v131
	v_cvt_pk_bf16_f32 v62, v62, v63
	ds_write_b16 v222, v62 offset:1664
	ds_write_b16_d16_hi v222, v62 offset:1728
	s_waitcnt lgkmcnt(0)
	ds_read_b128 v[132:135], v223
	ds_read_b128 v[136:139], v223 offset:1024
	s_waitcnt lgkmcnt(1)
	global_store_dwordx4 v224, v[132:135], s[78:79] offset:192
	s_waitcnt lgkmcnt(0)
	global_store_dwordx4 v229, v[136:139], s[78:79] offset:192
	s_add_i32 s26, s26, 1
	s_cmp_lt_u32 s26, 4
	s_cbranch_scc1 .Lat2_unit_1
	s_branch .Lat2_done_5
